# v34 + x-pass row sum-of-squares reduction via DPP (quad_perm/row mirrors) and permlane swaps instead of 6 serialized LDS bpermute round trips per row
# speedup vs baseline: 1.0091x; 1.0091x over previous
; __device__ __forceinline__ float wave_sum(float v) {
; #pragma unroll
;     for (int o = 1; o < 64; o <<= 1) v += __shfl_xor(v, o);
;     return v;
; }
; __device__ __forceinline__ void weights_phase(const In& I, unsigned char* ws, LAS unsigned char* lds, int tid, int lane, int wave, float* SW, int which) {
;     ...
;     for (int chunk = gw; chunk < M / 16; chunk += NGW) {
;         const int row0 = chunk * 16;
;         for (int r4 = 0; r4 < 16; r4 += 4) {
;             f32x4 v[4][4];
; #pragma unroll
;             for (int q = 0; q < 4; ++q) { const f32x4* xr = (const f32x4*)(I.x + (size_t)(row0 + r4 + q) * DM) + lane;
; #pragma unroll
;                 for (int j = 0; j < 4; ++j) v[q][j] = __builtin_nontemporal_load(xr + 64 * j); }
; #pragma unroll
;             for (int q = 0; q < 4; ++q) { float ssq = 0.f;
; #pragma unroll
;                 for (int j = 0; j < 4; ++j) ssq += (v[q][j].x * v[q][j].x + v[q][j].y * v[q][j].y) + (v[q][j].z * v[q][j].z + v[q][j].w * v[q][j].w);
;                 ssq = wave_sum(ssq);
;                 if (lane == 0) RSS[row0 + r4 + q] = ssq;
;                 u32x2* x8 = (u32x2*)(XB + (size_t)(row0 + r4 + q) * DM) + lane;
; #pragma unroll
;                 for (int j = 0; j < 4; ++j) { u32x2 xw; xw.x = cvt_pk_bf16(v[q][j].x, v[q][j].y); xw.y = cvt_pk_bf16(v[q][j].z, v[q][j].w); x8[64 * j] = xw; } }
.LBB0_49:
	s_add_i32 s26, s0, -15
	s_ashr_i32 s27, s26, 31
	s_lshl_b64 s[4:5], s[26:27], 12
	v_lshl_add_u64 v[0:1], v[66:67], 0, s[4:5]
	global_load_dwordx4 v[60:63], v[0:1], off nt
	global_load_dwordx4 v[56:59], v[0:1], off offset:1024 nt
	global_load_dwordx4 v[52:55], v[0:1], off offset:2048 nt
	global_load_dwordx4 v[48:51], v[0:1], off offset:3072 nt
	s_add_i32 s24, s0, -14
	s_add_i32 s6, s0, -13
	s_add_i32 s4, s0, -12
	s_ashr_i32 s25, s24, 31
	s_ashr_i32 s7, s6, 31
	s_ashr_i32 s5, s4, 31
	s_lshl_b64 s[14:15], s[24:25], 12
	s_lshl_b64 s[16:17], s[6:7], 12
	s_lshl_b64 s[18:19], s[4:5], 12
	v_lshl_add_u64 v[0:1], v[66:67], 0, s[14:15]
	v_lshl_add_u64 v[2:3], v[66:67], 0, s[16:17]
	v_lshl_add_u64 v[74:75], v[66:67], 0, s[18:19]
	global_load_dwordx4 v[44:47], v[0:1], off nt
	global_load_dwordx4 v[40:43], v[0:1], off offset:1024 nt
	global_load_dwordx4 v[36:39], v[0:1], off offset:2048 nt
	global_load_dwordx4 v[32:35], v[0:1], off offset:3072 nt
	global_load_dwordx4 v[28:31], v[2:3], off nt
	global_load_dwordx4 v[24:27], v[2:3], off offset:1024 nt
	s_waitcnt lgkmcnt(0)
	global_load_dwordx4 v[20:23], v[2:3], off offset:2048 nt
	global_load_dwordx4 v[16:19], v[2:3], off offset:3072 nt
	global_load_dwordx4 v[12:15], v[74:75], off nt
	global_load_dwordx4 v[8:11], v[74:75], off offset:1024 nt
	s_waitcnt lgkmcnt(0)
	global_load_dwordx4 v[4:7], v[74:75], off offset:2048 nt
	global_load_dwordx4 v[0:3], v[74:75], off offset:3072 nt
	s_waitcnt vmcnt(15)
	v_mul_f32_e32 v74, v61, v61
	v_mul_f32_e32 v75, v63, v63
	s_waitcnt vmcnt(14)
	v_mul_f32_e32 v76, v57, v57
	v_mul_f32_e32 v77, v59, v59
	s_waitcnt vmcnt(13)
	v_mul_f32_e32 v78, v53, v53
	v_mul_f32_e32 v79, v55, v55
	v_fmac_f32_e32 v74, v60, v60
	v_fmac_f32_e32 v75, v62, v62
	v_fmac_f32_e32 v76, v56, v56
	v_fmac_f32_e32 v77, v58, v58
	s_waitcnt vmcnt(12)
	v_mul_f32_e32 v80, v49, v49
	v_mul_f32_e32 v81, v51, v51
	v_fmac_f32_e32 v78, v52, v52
	v_fmac_f32_e32 v79, v54, v54
	v_add_f32_e32 v74, v74, v75
	v_add_f32_e32 v75, v76, v77
	v_fmac_f32_e32 v80, v48, v48
	v_fmac_f32_e32 v81, v50, v50
	v_add_f32_e32 v76, v78, v79
	v_add_f32_e32 v74, v74, v75
	v_add_f32_e32 v74, v74, v76
	v_add_f32_e32 v75, v80, v81
	v_add_f32_e32 v74, v74, v75
	s_nop 1
	v_mov_b32_dpp v75, v74 quad_perm:[1,0,3,2] row_mask:0xf bank_mask:0xf
	s_waitcnt lgkmcnt(0)
	v_add_f32_e32 v74, v74, v75
	s_nop 1
	v_mov_b32_dpp v75, v74 quad_perm:[2,3,0,1] row_mask:0xf bank_mask:0xf
	s_waitcnt lgkmcnt(0)
	v_add_f32_e32 v74, v74, v75
	s_nop 1
	v_mov_b32_dpp v75, v74 row_half_mirror row_mask:0xf bank_mask:0xf
	s_waitcnt lgkmcnt(0)
	v_add_f32_e32 v74, v74, v75
	s_nop 1
	v_mov_b32_dpp v75, v74 row_mirror row_mask:0xf bank_mask:0xf
	s_waitcnt lgkmcnt(0)
	v_add_f32_e32 v74, v74, v75
	v_mov_b32_e32 v75, v74
	s_nop 1
	v_permlane16_swap_b32_e32 v75, v74
	s_waitcnt lgkmcnt(0)
	v_add_f32_e32 v74, v74, v75
	v_mov_b32_e32 v75, v74
	s_nop 1
	v_permlane32_swap_b32_e32 v75, v74
	s_and_saveexec_b64 s[28:29], vcc
	s_cbranch_execz .LBB0_51
	s_lshl_b64 s[14:15], s[26:27], 2
	s_add_u32 s14, s8, s14
	s_waitcnt lgkmcnt(0)
	v_add_f32_e32 v74, v74, v75
	s_addc_u32 s15, s9, s15
	global_store_dword v169, v74, s[14:15]
.LBB0_51:
	s_or_b64 exec, exec, s[28:29]
	s_waitcnt vmcnt(11)
	v_mul_f32_e32 v74, v45, v45
	s_waitcnt lgkmcnt(0)
	v_mul_f32_e32 v75, v47, v47
	v_fmac_f32_e32 v74, v44, v44
	v_fmac_f32_e32 v75, v46, v46
	v_add_f32_e32 v74, v74, v75
	s_waitcnt vmcnt(10)
	v_mul_f32_e32 v75, v41, v41
	v_mul_f32_e32 v76, v43, v43
	v_fmac_f32_e32 v75, v40, v40
	v_fmac_f32_e32 v76, v42, v42
	v_add_f32_e32 v75, v75, v76
	v_add_f32_e32 v74, v74, v75
	s_waitcnt vmcnt(9)
	v_mul_f32_e32 v75, v37, v37
	v_mul_f32_e32 v76, v39, v39
	v_fmac_f32_e32 v75, v36, v36
	v_fmac_f32_e32 v76, v38, v38
	v_add_f32_e32 v75, v75, v76
	v_add_f32_e32 v74, v74, v75
	s_waitcnt vmcnt(8)
	v_mul_f32_e32 v75, v33, v33
	v_mul_f32_e32 v76, v35, v35
	v_fmac_f32_e32 v75, v32, v32
	v_fmac_f32_e32 v76, v34, v34
	v_add_f32_e32 v75, v75, v76
	v_add_f32_e32 v74, v74, v75
	s_nop 1
	v_mov_b32_dpp v75, v74 quad_perm:[1,0,3,2] row_mask:0xf bank_mask:0xf
	s_lshl_b64 s[14:15], s[26:27], 11
	v_cvt_pk_bf16_f32 v60, v60, v61
	v_cvt_pk_bf16_f32 v61, v62, v63
	v_cvt_pk_bf16_f32 v56, v56, v57
	s_waitcnt lgkmcnt(0)
	v_add_f32_e32 v74, v74, v75
	s_nop 1
	v_mov_b32_dpp v75, v74 quad_perm:[2,3,0,1] row_mask:0xf bank_mask:0xf
	v_cvt_pk_bf16_f32 v57, v58, v59
	v_cvt_pk_bf16_f32 v48, v48, v49
	v_cvt_pk_bf16_f32 v49, v50, v51
	s_waitcnt lgkmcnt(0)
	v_add_f32_e32 v76, v74, v75
	s_nop 1
	v_mov_b32_dpp v77, v76 row_half_mirror row_mask:0xf bank_mask:0xf
	v_lshl_add_u64 v[74:75], v[64:65], 0, s[14:15]
	global_store_dwordx2 v[74:75], v[60:61], off
	global_store_dwordx2 v[74:75], v[56:57], off offset:512
	v_cvt_pk_bf16_f32 v56, v52, v53
	s_waitcnt lgkmcnt(0)
	v_add_f32_e32 v76, v76, v77
	s_nop 1
	v_mov_b32_dpp v77, v76 row_mirror row_mask:0xf bank_mask:0xf
	v_cvt_pk_bf16_f32 v57, v54, v55
	global_store_dwordx2 v[74:75], v[56:57], off offset:1024
	global_store_dwordx2 v[74:75], v[48:49], off offset:1536
	s_waitcnt lgkmcnt(0)
	v_add_f32_e32 v60, v76, v77
	ds_bpermute_b32 v61, v72, v60
	s_waitcnt lgkmcnt(0)
	v_add_f32_e32 v52, v60, v61
	ds_bpermute_b32 v53, v73, v52
	s_and_saveexec_b64 s[26:27], vcc
	s_cbranch_execz .LBB0_53
	s_lshl_b64 s[14:15], s[24:25], 2
	s_add_u32 s14, s8, s14
	s_waitcnt lgkmcnt(0)
	v_add_f32_e32 v48, v52, v53
	s_addc_u32 s15, s9, s15
	global_store_dword v169, v48, s[14:15]
; __device__ __forceinline__ float wave_sum(float v) {
; #pragma unroll
;     for (int o = 1; o < 64; o <<= 1) v += __shfl_xor(v, o);
;     return v;
; }
; __device__ __forceinline__ void weights_phase(const In& I, unsigned char* ws, LAS unsigned char* lds, int tid, int lane, int wave, float* SW, int which) {
;     ...
;     for (int chunk = gw; chunk < M / 16; chunk += NGW) {
;         const int row0 = chunk * 16;
;         for (int r4 = 0; r4 < 16; r4 += 4) {
;             f32x4 v[4][4];
; #pragma unroll
;             for (int q = 0; q < 4; ++q) { const f32x4* xr = (const f32x4*)(I.x + (size_t)(row0 + r4 + q) * DM) + lane;
; #pragma unroll
;                 for (int j = 0; j < 4; ++j) v[q][j] = __builtin_nontemporal_load(xr + 64 * j); }
; #pragma unroll
;             for (int q = 0; q < 4; ++q) { float ssq = 0.f;
; #pragma unroll
;                 for (int j = 0; j < 4; ++j) ssq += (v[q][j].x * v[q][j].x + v[q][j].y * v[q][j].y) + (v[q][j].z * v[q][j].z + v[q][j].w * v[q][j].w);
;                 ssq = wave_sum(ssq);
;                 if (lane == 0) RSS[row0 + r4 + q] = ssq;
;                 u32x2* x8 = (u32x2*)(XB + (size_t)(row0 + r4 + q) * DM) + lane;
; #pragma unroll
;                 for (int j = 0; j < 4; ++j) { u32x2 xw; xw.x = cvt_pk_bf16(v[q][j].x, v[q][j].y); xw.y = cvt_pk_bf16(v[q][j].z, v[q][j].w); x8[64 * j] = xw; } }
.LBB0_53:
	s_or_b64 exec, exec, s[26:27]
	s_waitcnt vmcnt(11)
	v_mul_f32_e32 v48, v29, v29
	v_mul_f32_e32 v49, v31, v31
	v_fmac_f32_e32 v48, v28, v28
	v_fmac_f32_e32 v49, v30, v30
	v_add_f32_e32 v48, v48, v49
	s_waitcnt vmcnt(10)
	v_mul_f32_e32 v49, v25, v25
	v_mul_f32_e32 v50, v27, v27
	v_fmac_f32_e32 v49, v24, v24
	v_fmac_f32_e32 v50, v26, v26
	v_add_f32_e32 v49, v49, v50
	v_add_f32_e32 v48, v48, v49
	s_waitcnt vmcnt(9)
	v_mul_f32_e32 v49, v21, v21
	v_mul_f32_e32 v50, v23, v23
	v_fmac_f32_e32 v49, v20, v20
	v_fmac_f32_e32 v50, v22, v22
	v_add_f32_e32 v49, v49, v50
	v_add_f32_e32 v48, v48, v49
	s_waitcnt vmcnt(8)
	v_mul_f32_e32 v49, v17, v17
	v_mul_f32_e32 v50, v19, v19
	v_fmac_f32_e32 v49, v16, v16
	v_fmac_f32_e32 v50, v18, v18
	v_add_f32_e32 v49, v49, v50
	v_add_f32_e32 v48, v48, v49
	s_nop 1
	v_mov_b32_dpp v49, v48 quad_perm:[1,0,3,2] row_mask:0xf bank_mask:0xf
	s_lshl_b64 s[14:15], s[24:25], 11
	v_cvt_pk_bf16_f32 v44, v44, v45
	v_cvt_pk_bf16_f32 v45, v46, v47
	v_cvt_pk_bf16_f32 v40, v40, v41
	s_waitcnt lgkmcnt(0)
	v_add_f32_e32 v48, v48, v49
	s_nop 1
	v_mov_b32_dpp v49, v48 quad_perm:[2,3,0,1] row_mask:0xf bank_mask:0xf
	v_cvt_pk_bf16_f32 v41, v42, v43
	v_cvt_pk_bf16_f32 v32, v32, v33
	v_cvt_pk_bf16_f32 v33, v34, v35
	s_waitcnt lgkmcnt(0)
	v_add_f32_e32 v50, v48, v49
	s_nop 1
	v_mov_b32_dpp v51, v50 row_half_mirror row_mask:0xf bank_mask:0xf
	v_lshl_add_u64 v[48:49], v[64:65], 0, s[14:15]
	global_store_dwordx2 v[48:49], v[44:45], off
	global_store_dwordx2 v[48:49], v[40:41], off offset:512
	v_cvt_pk_bf16_f32 v40, v36, v37
	s_waitcnt lgkmcnt(0)
	v_add_f32_e32 v50, v50, v51
	s_nop 1
	v_mov_b32_dpp v51, v50 row_mirror row_mask:0xf bank_mask:0xf
	v_cvt_pk_bf16_f32 v41, v38, v39
	global_store_dwordx2 v[48:49], v[40:41], off offset:1024
	global_store_dwordx2 v[48:49], v[32:33], off offset:1536
	s_waitcnt lgkmcnt(0)
	v_add_f32_e32 v44, v50, v51
	ds_bpermute_b32 v45, v72, v44
	s_waitcnt lgkmcnt(0)
	v_add_f32_e32 v36, v44, v45
	ds_bpermute_b32 v37, v73, v36
	s_and_saveexec_b64 s[24:25], vcc
	s_cbranch_execz .LBB0_55
	s_lshl_b64 s[14:15], s[6:7], 2
	s_add_u32 s14, s8, s14
	s_waitcnt lgkmcnt(0)
	v_add_f32_e32 v32, v36, v37
	s_addc_u32 s15, s9, s15
	global_store_dword v169, v32, s[14:15]
.LBB0_55:
	s_or_b64 exec, exec, s[24:25]
	s_waitcnt vmcnt(11)
	v_mul_f32_e32 v32, v13, v13
	v_mul_f32_e32 v33, v15, v15
	v_fmac_f32_e32 v32, v12, v12
	v_fmac_f32_e32 v33, v14, v14
	v_add_f32_e32 v32, v32, v33
	s_waitcnt vmcnt(10)
	v_mul_f32_e32 v33, v9, v9
	v_mul_f32_e32 v34, v11, v11
	v_fmac_f32_e32 v33, v8, v8
	v_fmac_f32_e32 v34, v10, v10
	v_add_f32_e32 v33, v33, v34
	v_add_f32_e32 v32, v32, v33
	s_waitcnt vmcnt(9)
	v_mul_f32_e32 v33, v5, v5
	v_mul_f32_e32 v34, v7, v7
	v_fmac_f32_e32 v33, v4, v4
	v_fmac_f32_e32 v34, v6, v6
	v_add_f32_e32 v33, v33, v34
	v_add_f32_e32 v32, v32, v33
	s_waitcnt vmcnt(8)
	v_mul_f32_e32 v33, v1, v1
	v_mul_f32_e32 v34, v3, v3
	v_fmac_f32_e32 v33, v0, v0
	v_fmac_f32_e32 v34, v2, v2
	v_add_f32_e32 v33, v33, v34
	v_add_f32_e32 v32, v32, v33
	s_nop 1
	v_mov_b32_dpp v33, v32 quad_perm:[1,0,3,2] row_mask:0xf bank_mask:0xf
	s_lshl_b64 s[6:7], s[6:7], 11
	v_cvt_pk_bf16_f32 v28, v28, v29
	v_cvt_pk_bf16_f32 v29, v30, v31
	v_cvt_pk_bf16_f32 v24, v24, v25
	s_waitcnt lgkmcnt(0)
	v_add_f32_e32 v32, v32, v33
	s_nop 1
	v_mov_b32_dpp v33, v32 quad_perm:[2,3,0,1] row_mask:0xf bank_mask:0xf
	v_cvt_pk_bf16_f32 v25, v26, v27
	v_cvt_pk_bf16_f32 v16, v16, v17
	v_cvt_pk_bf16_f32 v17, v18, v19
	s_waitcnt lgkmcnt(0)
	v_add_f32_e32 v34, v32, v33
	s_nop 1
	v_mov_b32_dpp v35, v34 row_half_mirror row_mask:0xf bank_mask:0xf
	v_lshl_add_u64 v[32:33], v[64:65], 0, s[6:7]
	global_store_dwordx2 v[32:33], v[28:29], off
	global_store_dwordx2 v[32:33], v[24:25], off offset:512
	v_cvt_pk_bf16_f32 v24, v20, v21
	s_waitcnt lgkmcnt(0)
	v_add_f32_e32 v34, v34, v35
	s_nop 1
	v_mov_b32_dpp v35, v34 row_mirror row_mask:0xf bank_mask:0xf
	v_cvt_pk_bf16_f32 v25, v22, v23
	global_store_dwordx2 v[32:33], v[24:25], off offset:1024
	global_store_dwordx2 v[32:33], v[16:17], off offset:1536
	s_waitcnt lgkmcnt(0)
	v_add_f32_e32 v28, v34, v35
	v_mov_b32_e32 v29, v28
	s_nop 1
	v_permlane16_swap_b32_e32 v29, v28
	s_waitcnt lgkmcnt(0)
	v_add_f32_e32 v20, v28, v29
	v_mov_b32_e32 v21, v20
	s_nop 1
	v_permlane32_swap_b32_e32 v21, v20
	s_and_saveexec_b64 s[6:7], vcc
	s_cbranch_execz .LBB0_57
	s_lshl_b64 s[14:15], s[4:5], 2
	s_add_u32 s14, s8, s14
	s_waitcnt lgkmcnt(0)
	v_add_f32_e32 v16, v20, v21
	s_addc_u32 s15, s9, s15
	global_store_dword v169, v16, s[14:15]
; __device__ __forceinline__ float wave_sum(float v) {
; #pragma unroll
;     for (int o = 1; o < 64; o <<= 1) v += __shfl_xor(v, o);
;     return v;
; }
; __device__ __forceinline__ void weights_phase(const In& I, unsigned char* ws, LAS unsigned char* lds, int tid, int lane, int wave, float* SW, int which) {
;     ...
;     for (int chunk = gw; chunk < M / 16; chunk += NGW) {
;         const int row0 = chunk * 16;
;         for (int r4 = 0; r4 < 16; r4 += 4) {
;             f32x4 v[4][4];
; #pragma unroll
;             for (int q = 0; q < 4; ++q) { const f32x4* xr = (const f32x4*)(I.x + (size_t)(row0 + r4 + q) * DM) + lane;
; #pragma unroll
;                 for (int j = 0; j < 4; ++j) v[q][j] = __builtin_nontemporal_load(xr + 64 * j); }
; #pragma unroll
;             for (int q = 0; q < 4; ++q) { float ssq = 0.f;
; #pragma unroll
;                 for (int j = 0; j < 4; ++j) ssq += (v[q][j].x * v[q][j].x + v[q][j].y * v[q][j].y) + (v[q][j].z * v[q][j].z + v[q][j].w * v[q][j].w);
;                 ssq = wave_sum(ssq);
;                 if (lane == 0) RSS[row0 + r4 + q] = ssq;
;                 u32x2* x8 = (u32x2*)(XB + (size_t)(row0 + r4 + q) * DM) + lane;
; #pragma unroll
;                 for (int j = 0; j < 4; ++j) { u32x2 xw; xw.x = cvt_pk_bf16(v[q][j].x, v[q][j].y); xw.y = cvt_pk_bf16(v[q][j].z, v[q][j].w); x8[64 * j] = xw; } }
.LBB0_57:
	s_or_b64 exec, exec, s[6:7]
	s_add_i32 s26, s0, -11
	s_lshl_b64 s[4:5], s[4:5], 11
	s_ashr_i32 s27, s26, 31
	v_lshl_add_u64 v[16:17], v[64:65], 0, s[4:5]
	v_cvt_pk_bf16_f32 v12, v12, v13
	v_cvt_pk_bf16_f32 v13, v14, v15
	v_cvt_pk_bf16_f32 v8, v8, v9
	v_cvt_pk_bf16_f32 v9, v10, v11
	v_cvt_pk_bf16_f32 v4, v4, v5
	v_cvt_pk_bf16_f32 v5, v6, v7
	v_cvt_pk_bf16_f32 v0, v0, v1
	v_cvt_pk_bf16_f32 v1, v2, v3
	s_lshl_b64 s[4:5], s[26:27], 12
	global_store_dwordx2 v[16:17], v[12:13], off
	global_store_dwordx2 v[16:17], v[8:9], off offset:512
	global_store_dwordx2 v[16:17], v[4:5], off offset:1024
	global_store_dwordx2 v[16:17], v[0:1], off offset:1536
	v_lshl_add_u64 v[0:1], v[66:67], 0, s[4:5]
	global_load_dwordx4 v[60:63], v[0:1], off nt
	global_load_dwordx4 v[56:59], v[0:1], off offset:1024 nt
	global_load_dwordx4 v[52:55], v[0:1], off offset:2048 nt
	global_load_dwordx4 v[48:51], v[0:1], off offset:3072 nt
	s_add_i32 s24, s0, -10
	s_add_i32 s6, s0, -9
	s_add_i32 s4, s0, -8
	s_ashr_i32 s25, s24, 31
	s_ashr_i32 s7, s6, 31
	s_ashr_i32 s5, s4, 31
	s_lshl_b64 s[14:15], s[24:25], 12
	s_lshl_b64 s[16:17], s[6:7], 12
	s_lshl_b64 s[18:19], s[4:5], 12
	v_lshl_add_u64 v[0:1], v[66:67], 0, s[14:15]
	v_lshl_add_u64 v[2:3], v[66:67], 0, s[16:17]
	v_lshl_add_u64 v[74:75], v[66:67], 0, s[18:19]
	global_load_dwordx4 v[44:47], v[0:1], off nt
	global_load_dwordx4 v[40:43], v[0:1], off offset:1024 nt
	global_load_dwordx4 v[36:39], v[0:1], off offset:2048 nt
	global_load_dwordx4 v[32:35], v[0:1], off offset:3072 nt
	global_load_dwordx4 v[28:31], v[2:3], off nt
	global_load_dwordx4 v[24:27], v[2:3], off offset:1024 nt
	s_waitcnt lgkmcnt(0)
	global_load_dwordx4 v[20:23], v[2:3], off offset:2048 nt
	global_load_dwordx4 v[16:19], v[2:3], off offset:3072 nt
	global_load_dwordx4 v[12:15], v[74:75], off nt
	global_load_dwordx4 v[8:11], v[74:75], off offset:1024 nt
	global_load_dwordx4 v[4:7], v[74:75], off offset:2048 nt
	s_nop 0
	global_load_dwordx4 v[0:3], v[74:75], off offset:3072 nt
	s_waitcnt vmcnt(15)
	v_mul_f32_e32 v74, v61, v61
	v_mul_f32_e32 v75, v63, v63
	s_waitcnt vmcnt(14)
	v_mul_f32_e32 v76, v57, v57
	v_mul_f32_e32 v77, v59, v59
	s_waitcnt vmcnt(13)
	v_mul_f32_e32 v78, v53, v53
	v_mul_f32_e32 v79, v55, v55
	v_fmac_f32_e32 v74, v60, v60
	v_fmac_f32_e32 v75, v62, v62
	v_fmac_f32_e32 v76, v56, v56
	v_fmac_f32_e32 v77, v58, v58
	s_waitcnt vmcnt(12)
	v_mul_f32_e32 v80, v49, v49
	v_mul_f32_e32 v81, v51, v51
	v_fmac_f32_e32 v78, v52, v52
	v_fmac_f32_e32 v79, v54, v54
	v_add_f32_e32 v74, v74, v75
	v_add_f32_e32 v75, v76, v77
	v_fmac_f32_e32 v80, v48, v48
	v_fmac_f32_e32 v81, v50, v50
	v_add_f32_e32 v76, v78, v79
	v_add_f32_e32 v74, v74, v75
	v_add_f32_e32 v74, v74, v76
	v_add_f32_e32 v75, v80, v81
	v_add_f32_e32 v74, v74, v75
	s_nop 1
	v_mov_b32_dpp v75, v74 quad_perm:[1,0,3,2] row_mask:0xf bank_mask:0xf
	s_waitcnt lgkmcnt(0)
	v_add_f32_e32 v74, v74, v75
	s_nop 1
	v_mov_b32_dpp v75, v74 quad_perm:[2,3,0,1] row_mask:0xf bank_mask:0xf
	s_waitcnt lgkmcnt(0)
	v_add_f32_e32 v74, v74, v75
	s_nop 1
	v_mov_b32_dpp v75, v74 row_half_mirror row_mask:0xf bank_mask:0xf
	s_waitcnt lgkmcnt(0)
	v_add_f32_e32 v74, v74, v75
	s_nop 1
	v_mov_b32_dpp v75, v74 row_mirror row_mask:0xf bank_mask:0xf
	s_waitcnt lgkmcnt(0)
	v_add_f32_e32 v74, v74, v75
	v_mov_b32_e32 v75, v74
	s_nop 1
	v_permlane16_swap_b32_e32 v75, v74
	s_waitcnt lgkmcnt(0)
	v_add_f32_e32 v74, v74, v75
	v_mov_b32_e32 v75, v74
	s_nop 1
	v_permlane32_swap_b32_e32 v75, v74
	s_and_saveexec_b64 s[28:29], vcc
	s_cbranch_execz .LBB0_59
	s_lshl_b64 s[14:15], s[26:27], 2
	s_add_u32 s14, s8, s14
	s_waitcnt lgkmcnt(0)
	v_add_f32_e32 v74, v74, v75
	s_addc_u32 s15, s9, s15
	global_store_dword v169, v74, s[14:15]

; __device__ __forceinline__ float wave_sum(float v) {
; #pragma unroll
;     for (int o = 1; o < 64; o <<= 1) v += __shfl_xor(v, o);
;     return v;
; }
; __device__ __forceinline__ void weights_phase(const In& I, unsigned char* ws, LAS unsigned char* lds, int tid, int lane, int wave, float* SW, int which) {
;     ...
;     for (int chunk = gw; chunk < M / 16; chunk += NGW) {
;         const int row0 = chunk * 16;
;         for (int r4 = 0; r4 < 16; r4 += 4) {
;             f32x4 v[4][4];
; #pragma unroll
;             for (int q = 0; q < 4; ++q) { const f32x4* xr = (const f32x4*)(I.x + (size_t)(row0 + r4 + q) * DM) + lane;
; #pragma unroll
;                 for (int j = 0; j < 4; ++j) v[q][j] = __builtin_nontemporal_load(xr + 64 * j); }
; #pragma unroll
;             for (int q = 0; q < 4; ++q) { float ssq = 0.f;
; #pragma unroll
;                 for (int j = 0; j < 4; ++j) ssq += (v[q][j].x * v[q][j].x + v[q][j].y * v[q][j].y) + (v[q][j].z * v[q][j].z + v[q][j].w * v[q][j].w);
;                 ssq = wave_sum(ssq);
;                 if (lane == 0) RSS[row0 + r4 + q] = ssq;
;                 u32x2* x8 = (u32x2*)(XB + (size_t)(row0 + r4 + q) * DM) + lane;
; #pragma unroll
;                 for (int j = 0; j < 4; ++j) { u32x2 xw; xw.x = cvt_pk_bf16(v[q][j].x, v[q][j].y); xw.y = cvt_pk_bf16(v[q][j].z, v[q][j].w); x8[64 * j] = xw; } }
.LBB0_65:
	s_or_b64 exec, exec, s[6:7]
	s_add_i32 s26, s0, -7
	s_lshl_b64 s[4:5], s[4:5], 11
	s_ashr_i32 s27, s26, 31
	v_lshl_add_u64 v[16:17], v[64:65], 0, s[4:5]
	v_cvt_pk_bf16_f32 v12, v12, v13
	v_cvt_pk_bf16_f32 v13, v14, v15
	v_cvt_pk_bf16_f32 v8, v8, v9
	v_cvt_pk_bf16_f32 v9, v10, v11
	v_cvt_pk_bf16_f32 v4, v4, v5
	v_cvt_pk_bf16_f32 v5, v6, v7
	v_cvt_pk_bf16_f32 v0, v0, v1
	v_cvt_pk_bf16_f32 v1, v2, v3
	s_lshl_b64 s[4:5], s[26:27], 12
	global_store_dwordx2 v[16:17], v[12:13], off
	global_store_dwordx2 v[16:17], v[8:9], off offset:512
	global_store_dwordx2 v[16:17], v[4:5], off offset:1024
	global_store_dwordx2 v[16:17], v[0:1], off offset:1536
	v_lshl_add_u64 v[0:1], v[66:67], 0, s[4:5]
	global_load_dwordx4 v[60:63], v[0:1], off nt
	global_load_dwordx4 v[56:59], v[0:1], off offset:1024 nt
	global_load_dwordx4 v[52:55], v[0:1], off offset:2048 nt
	global_load_dwordx4 v[48:51], v[0:1], off offset:3072 nt
	s_add_i32 s24, s0, -6
	s_add_i32 s6, s0, -5
	s_add_i32 s4, s0, -4
	s_ashr_i32 s25, s24, 31
	s_ashr_i32 s7, s6, 31
	s_ashr_i32 s5, s4, 31
	s_lshl_b64 s[14:15], s[24:25], 12
	s_lshl_b64 s[16:17], s[6:7], 12
	s_lshl_b64 s[18:19], s[4:5], 12
	v_lshl_add_u64 v[0:1], v[66:67], 0, s[14:15]
	v_lshl_add_u64 v[2:3], v[66:67], 0, s[16:17]
	v_lshl_add_u64 v[74:75], v[66:67], 0, s[18:19]
	global_load_dwordx4 v[44:47], v[0:1], off nt
	global_load_dwordx4 v[40:43], v[0:1], off offset:1024 nt
	global_load_dwordx4 v[36:39], v[0:1], off offset:2048 nt
	global_load_dwordx4 v[32:35], v[0:1], off offset:3072 nt
	global_load_dwordx4 v[28:31], v[2:3], off nt
	global_load_dwordx4 v[24:27], v[2:3], off offset:1024 nt
	s_waitcnt lgkmcnt(0)
	global_load_dwordx4 v[20:23], v[2:3], off offset:2048 nt
	global_load_dwordx4 v[16:19], v[2:3], off offset:3072 nt
	global_load_dwordx4 v[12:15], v[74:75], off nt
	global_load_dwordx4 v[8:11], v[74:75], off offset:1024 nt
	global_load_dwordx4 v[4:7], v[74:75], off offset:2048 nt
	s_nop 0
	global_load_dwordx4 v[0:3], v[74:75], off offset:3072 nt
	s_waitcnt vmcnt(15)
	v_mul_f32_e32 v74, v61, v61
	v_mul_f32_e32 v75, v63, v63
	s_waitcnt vmcnt(14)
	v_mul_f32_e32 v76, v57, v57
	v_mul_f32_e32 v77, v59, v59
	s_waitcnt vmcnt(13)
	v_mul_f32_e32 v78, v53, v53
	v_mul_f32_e32 v79, v55, v55
	v_fmac_f32_e32 v74, v60, v60
	v_fmac_f32_e32 v75, v62, v62
	v_fmac_f32_e32 v76, v56, v56
	v_fmac_f32_e32 v77, v58, v58
	s_waitcnt vmcnt(12)
	v_mul_f32_e32 v80, v49, v49
	v_mul_f32_e32 v81, v51, v51
	v_fmac_f32_e32 v78, v52, v52
	v_fmac_f32_e32 v79, v54, v54
	v_add_f32_e32 v74, v74, v75
	v_add_f32_e32 v75, v76, v77
	v_fmac_f32_e32 v80, v48, v48
	v_fmac_f32_e32 v81, v50, v50
	v_add_f32_e32 v76, v78, v79
	v_add_f32_e32 v74, v74, v75
	v_add_f32_e32 v74, v74, v76
	v_add_f32_e32 v75, v80, v81
	v_add_f32_e32 v74, v74, v75
	s_nop 1
	v_mov_b32_dpp v75, v74 quad_perm:[1,0,3,2] row_mask:0xf bank_mask:0xf
	s_waitcnt lgkmcnt(0)
	v_add_f32_e32 v74, v74, v75
	s_nop 1
	v_mov_b32_dpp v75, v74 quad_perm:[2,3,0,1] row_mask:0xf bank_mask:0xf
	s_waitcnt lgkmcnt(0)
	v_add_f32_e32 v74, v74, v75
	s_nop 1
	v_mov_b32_dpp v75, v74 row_half_mirror row_mask:0xf bank_mask:0xf
	s_waitcnt lgkmcnt(0)
	v_add_f32_e32 v74, v74, v75
	s_nop 1
	v_mov_b32_dpp v75, v74 row_mirror row_mask:0xf bank_mask:0xf
	s_waitcnt lgkmcnt(0)
	v_add_f32_e32 v74, v74, v75
	v_mov_b32_e32 v75, v74
	s_nop 1
	v_permlane16_swap_b32_e32 v75, v74
	s_waitcnt lgkmcnt(0)
	v_add_f32_e32 v74, v74, v75
	v_mov_b32_e32 v75, v74
	s_nop 1
	v_permlane32_swap_b32_e32 v75, v74
	s_and_saveexec_b64 s[28:29], vcc
	s_cbranch_execz .LBB0_67
	s_lshl_b64 s[14:15], s[26:27], 2
	s_add_u32 s14, s8, s14
	s_waitcnt lgkmcnt(0)
	v_add_f32_e32 v74, v74, v75
	s_addc_u32 s15, s9, s15
	global_store_dword v169, v74, s[14:15]

; __device__ __forceinline__ float wave_sum(float v) {
; #pragma unroll
;     for (int o = 1; o < 64; o <<= 1) v += __shfl_xor(v, o);
;     return v;
; }
; __device__ __forceinline__ void weights_phase(const In& I, unsigned char* ws, LAS unsigned char* lds, int tid, int lane, int wave, float* SW, int which) {
;     ...
;     for (int chunk = gw; chunk < M / 16; chunk += NGW) {
;         const int row0 = chunk * 16;
;         for (int r4 = 0; r4 < 16; r4 += 4) {
;             f32x4 v[4][4];
; #pragma unroll
;             for (int q = 0; q < 4; ++q) { const f32x4* xr = (const f32x4*)(I.x + (size_t)(row0 + r4 + q) * DM) + lane;
; #pragma unroll
;                 for (int j = 0; j < 4; ++j) v[q][j] = __builtin_nontemporal_load(xr + 64 * j); }
; #pragma unroll
;             for (int q = 0; q < 4; ++q) { float ssq = 0.f;
; #pragma unroll
;                 for (int j = 0; j < 4; ++j) ssq += (v[q][j].x * v[q][j].x + v[q][j].y * v[q][j].y) + (v[q][j].z * v[q][j].z + v[q][j].w * v[q][j].w);
;                 ssq = wave_sum(ssq);
;                 if (lane == 0) RSS[row0 + r4 + q] = ssq;
;                 u32x2* x8 = (u32x2*)(XB + (size_t)(row0 + r4 + q) * DM) + lane;
; #pragma unroll
;                 for (int j = 0; j < 4; ++j) { u32x2 xw; xw.x = cvt_pk_bf16(v[q][j].x, v[q][j].y); xw.y = cvt_pk_bf16(v[q][j].z, v[q][j].w); x8[64 * j] = xw; } }
.LBB0_73:
	s_or_b64 exec, exec, s[6:7]
	s_add_i32 s24, s0, -3
	s_lshl_b64 s[4:5], s[4:5], 11
	s_ashr_i32 s25, s24, 31
	v_lshl_add_u64 v[16:17], v[64:65], 0, s[4:5]
	v_cvt_pk_bf16_f32 v12, v12, v13
	v_cvt_pk_bf16_f32 v13, v14, v15
	v_cvt_pk_bf16_f32 v8, v8, v9
	v_cvt_pk_bf16_f32 v9, v10, v11
	v_cvt_pk_bf16_f32 v4, v4, v5
	v_cvt_pk_bf16_f32 v5, v6, v7
	v_cvt_pk_bf16_f32 v0, v0, v1
	v_cvt_pk_bf16_f32 v1, v2, v3
	s_lshl_b64 s[4:5], s[24:25], 12
	global_store_dwordx2 v[16:17], v[12:13], off
	global_store_dwordx2 v[16:17], v[8:9], off offset:512
	global_store_dwordx2 v[16:17], v[4:5], off offset:1024
	global_store_dwordx2 v[16:17], v[0:1], off offset:1536
	v_lshl_add_u64 v[0:1], v[66:67], 0, s[4:5]
	global_load_dwordx4 v[60:63], v[0:1], off nt
	global_load_dwordx4 v[56:59], v[0:1], off offset:1024 nt
	global_load_dwordx4 v[52:55], v[0:1], off offset:2048 nt
	global_load_dwordx4 v[48:51], v[0:1], off offset:3072 nt
	s_add_i32 s6, s0, -2
	s_add_i32 s4, s0, -1
	s_ashr_i32 s1, s0, 31
	s_ashr_i32 s7, s6, 31
	s_ashr_i32 s5, s4, 31
	s_lshl_b64 s[14:15], s[0:1], 12
	s_lshl_b64 s[16:17], s[6:7], 12
	s_lshl_b64 s[18:19], s[4:5], 12
	v_lshl_add_u64 v[0:1], v[66:67], 0, s[14:15]
	v_lshl_add_u64 v[16:17], v[66:67], 0, s[16:17]
	v_lshl_add_u64 v[18:19], v[66:67], 0, s[18:19]
	global_load_dwordx4 v[12:15], v[0:1], off nt
	global_load_dwordx4 v[8:11], v[0:1], off offset:1024 nt
	global_load_dwordx4 v[4:7], v[0:1], off offset:2048 nt
	s_nop 0
	global_load_dwordx4 v[0:3], v[0:1], off offset:3072 nt
	s_nop 0
	global_load_dwordx4 v[44:47], v[16:17], off nt
	global_load_dwordx4 v[40:43], v[16:17], off offset:1024 nt
	global_load_dwordx4 v[36:39], v[16:17], off offset:2048 nt
	global_load_dwordx4 v[32:35], v[16:17], off offset:3072 nt
	global_load_dwordx4 v[28:31], v[18:19], off nt
	global_load_dwordx4 v[24:27], v[18:19], off offset:1024 nt
	s_waitcnt lgkmcnt(0)
	global_load_dwordx4 v[20:23], v[18:19], off offset:2048 nt
	s_nop 0
	global_load_dwordx4 v[16:19], v[18:19], off offset:3072 nt
	s_waitcnt vmcnt(15)
	v_mul_f32_e32 v74, v61, v61
	v_mul_f32_e32 v75, v63, v63
	s_waitcnt vmcnt(14)
	v_mul_f32_e32 v76, v57, v57
	v_mul_f32_e32 v77, v59, v59
	s_waitcnt vmcnt(13)
	v_mul_f32_e32 v78, v53, v53
	v_mul_f32_e32 v79, v55, v55
	v_fmac_f32_e32 v74, v60, v60
	v_fmac_f32_e32 v75, v62, v62
	v_fmac_f32_e32 v76, v56, v56
	v_fmac_f32_e32 v77, v58, v58
	s_waitcnt vmcnt(12)
	v_mul_f32_e32 v80, v49, v49
	v_mul_f32_e32 v81, v51, v51
	v_fmac_f32_e32 v78, v52, v52
	v_fmac_f32_e32 v79, v54, v54
	v_add_f32_e32 v74, v74, v75
	v_add_f32_e32 v75, v76, v77
	v_fmac_f32_e32 v80, v48, v48
	v_fmac_f32_e32 v81, v50, v50
	v_add_f32_e32 v76, v78, v79
	v_add_f32_e32 v74, v74, v75
	v_add_f32_e32 v74, v74, v76
	v_add_f32_e32 v75, v80, v81
	v_add_f32_e32 v74, v74, v75
	s_nop 1
	v_mov_b32_dpp v75, v74 quad_perm:[1,0,3,2] row_mask:0xf bank_mask:0xf
	s_waitcnt lgkmcnt(0)
	v_add_f32_e32 v74, v74, v75
	s_nop 1
	v_mov_b32_dpp v75, v74 quad_perm:[2,3,0,1] row_mask:0xf bank_mask:0xf
	s_waitcnt lgkmcnt(0)
	v_add_f32_e32 v74, v74, v75
	s_nop 1
	v_mov_b32_dpp v75, v74 row_half_mirror row_mask:0xf bank_mask:0xf
	s_waitcnt lgkmcnt(0)
	v_add_f32_e32 v74, v74, v75
	s_nop 1
	v_mov_b32_dpp v75, v74 row_mirror row_mask:0xf bank_mask:0xf
	s_waitcnt lgkmcnt(0)
	v_add_f32_e32 v74, v74, v75
	v_mov_b32_e32 v75, v74
	s_nop 1
	v_permlane16_swap_b32_e32 v75, v74
	s_waitcnt lgkmcnt(0)
	v_add_f32_e32 v74, v74, v75
	v_mov_b32_e32 v75, v74
	s_nop 1
	v_permlane32_swap_b32_e32 v75, v74
	s_and_saveexec_b64 s[26:27], vcc
	s_cbranch_execz .LBB0_75
	s_lshl_b64 s[14:15], s[24:25], 2
	s_add_u32 s14, s8, s14
	s_waitcnt lgkmcnt(0)
	v_add_f32_e32 v74, v74, v75
	s_addc_u32 s15, s9, s15
	global_store_dword v169, v74, s[14:15]
.LBB0_75:
	s_or_b64 exec, exec, s[26:27]
	s_waitcnt vmcnt(7)
	v_mul_f32_e32 v74, v45, v45
	s_waitcnt lgkmcnt(0)
	v_mul_f32_e32 v75, v47, v47
	v_fmac_f32_e32 v74, v44, v44
	v_fmac_f32_e32 v75, v46, v46
	v_add_f32_e32 v74, v74, v75
	s_waitcnt vmcnt(6)
	v_mul_f32_e32 v75, v41, v41
	v_mul_f32_e32 v76, v43, v43
	v_fmac_f32_e32 v75, v40, v40
	v_fmac_f32_e32 v76, v42, v42
	v_add_f32_e32 v75, v75, v76
	v_add_f32_e32 v74, v74, v75
	s_waitcnt vmcnt(5)
	v_mul_f32_e32 v75, v37, v37
	v_mul_f32_e32 v76, v39, v39
	v_fmac_f32_e32 v75, v36, v36
	v_fmac_f32_e32 v76, v38, v38
	v_add_f32_e32 v75, v75, v76
	v_add_f32_e32 v74, v74, v75
	s_waitcnt vmcnt(4)
	v_mul_f32_e32 v75, v33, v33
	v_mul_f32_e32 v76, v35, v35
	v_fmac_f32_e32 v75, v32, v32
	v_fmac_f32_e32 v76, v34, v34
	v_add_f32_e32 v75, v75, v76
	v_add_f32_e32 v74, v74, v75
	s_nop 1
	v_mov_b32_dpp v75, v74 quad_perm:[1,0,3,2] row_mask:0xf bank_mask:0xf
	s_lshl_b64 s[14:15], s[24:25], 11
	v_cvt_pk_bf16_f32 v60, v60, v61
	v_cvt_pk_bf16_f32 v61, v62, v63
	v_cvt_pk_bf16_f32 v56, v56, v57
	s_waitcnt lgkmcnt(0)
	v_add_f32_e32 v74, v74, v75
	s_nop 1
	v_mov_b32_dpp v75, v74 quad_perm:[2,3,0,1] row_mask:0xf bank_mask:0xf
	v_cvt_pk_bf16_f32 v57, v58, v59
	v_cvt_pk_bf16_f32 v48, v48, v49
	v_cvt_pk_bf16_f32 v49, v50, v51
	s_waitcnt lgkmcnt(0)
	v_add_f32_e32 v76, v74, v75
	s_nop 1
	v_mov_b32_dpp v77, v76 row_half_mirror row_mask:0xf bank_mask:0xf
	v_lshl_add_u64 v[74:75], v[64:65], 0, s[14:15]
	global_store_dwordx2 v[74:75], v[60:61], off
	global_store_dwordx2 v[74:75], v[56:57], off offset:512
	v_cvt_pk_bf16_f32 v56, v52, v53
	s_waitcnt lgkmcnt(0)
	v_add_f32_e32 v76, v76, v77
	s_nop 1
	v_mov_b32_dpp v77, v76 row_mirror row_mask:0xf bank_mask:0xf
	v_cvt_pk_bf16_f32 v57, v54, v55
	global_store_dwordx2 v[74:75], v[56:57], off offset:1024
	global_store_dwordx2 v[74:75], v[48:49], off offset:1536
	s_waitcnt lgkmcnt(0)
	v_add_f32_e32 v60, v76, v77
	ds_bpermute_b32 v61, v72, v60
	s_waitcnt lgkmcnt(0)
	v_add_f32_e32 v52, v60, v61
	ds_bpermute_b32 v53, v73, v52
	s_and_saveexec_b64 s[24:25], vcc
	s_cbranch_execz .LBB0_77
	s_lshl_b64 s[14:15], s[6:7], 2
	s_add_u32 s14, s8, s14
	s_waitcnt lgkmcnt(0)
	v_add_f32_e32 v48, v52, v53
	s_addc_u32 s15, s9, s15
	global_store_dword v169, v48, s[14:15]
; __device__ __forceinline__ float wave_sum(float v) {
; #pragma unroll
;     for (int o = 1; o < 64; o <<= 1) v += __shfl_xor(v, o);
;     return v;
; }
; __device__ __forceinline__ void weights_phase(const In& I, unsigned char* ws, LAS unsigned char* lds, int tid, int lane, int wave, float* SW, int which) {
;     ...
;     for (int chunk = gw; chunk < M / 16; chunk += NGW) {
;         const int row0 = chunk * 16;
;         for (int r4 = 0; r4 < 16; r4 += 4) {
;             f32x4 v[4][4];
; #pragma unroll
;             for (int q = 0; q < 4; ++q) { const f32x4* xr = (const f32x4*)(I.x + (size_t)(row0 + r4 + q) * DM) + lane;
; #pragma unroll
;                 for (int j = 0; j < 4; ++j) v[q][j] = __builtin_nontemporal_load(xr + 64 * j); }
; #pragma unroll
;             for (int q = 0; q < 4; ++q) { float ssq = 0.f;
; #pragma unroll
;                 for (int j = 0; j < 4; ++j) ssq += (v[q][j].x * v[q][j].x + v[q][j].y * v[q][j].y) + (v[q][j].z * v[q][j].z + v[q][j].w * v[q][j].w);
;                 ssq = wave_sum(ssq);
;                 if (lane == 0) RSS[row0 + r4 + q] = ssq;
;                 u32x2* x8 = (u32x2*)(XB + (size_t)(row0 + r4 + q) * DM) + lane;
; #pragma unroll
;                 for (int j = 0; j < 4; ++j) { u32x2 xw; xw.x = cvt_pk_bf16(v[q][j].x, v[q][j].y); xw.y = cvt_pk_bf16(v[q][j].z, v[q][j].w); x8[64 * j] = xw; } }
.LBB0_77:
	s_or_b64 exec, exec, s[24:25]
	s_waitcnt vmcnt(7)
	v_mul_f32_e32 v48, v29, v29
	v_mul_f32_e32 v49, v31, v31
	v_fmac_f32_e32 v48, v28, v28
	v_fmac_f32_e32 v49, v30, v30
	v_add_f32_e32 v48, v48, v49
	s_waitcnt vmcnt(6)
	v_mul_f32_e32 v49, v25, v25
	v_mul_f32_e32 v50, v27, v27
	v_fmac_f32_e32 v49, v24, v24
	v_fmac_f32_e32 v50, v26, v26
	v_add_f32_e32 v49, v49, v50
	v_add_f32_e32 v48, v48, v49
	s_waitcnt vmcnt(5)
	v_mul_f32_e32 v49, v21, v21
	v_mul_f32_e32 v50, v23, v23
	v_fmac_f32_e32 v49, v20, v20
	v_fmac_f32_e32 v50, v22, v22
	v_add_f32_e32 v49, v49, v50
	v_add_f32_e32 v48, v48, v49
	s_waitcnt vmcnt(4)
	v_mul_f32_e32 v49, v17, v17
	v_mul_f32_e32 v50, v19, v19
	v_fmac_f32_e32 v49, v16, v16
	v_fmac_f32_e32 v50, v18, v18
	v_add_f32_e32 v49, v49, v50
	v_add_f32_e32 v48, v48, v49
	s_nop 1
	v_mov_b32_dpp v49, v48 quad_perm:[1,0,3,2] row_mask:0xf bank_mask:0xf
	s_lshl_b64 s[6:7], s[6:7], 11
	v_cvt_pk_bf16_f32 v44, v44, v45
	v_cvt_pk_bf16_f32 v45, v46, v47
	v_cvt_pk_bf16_f32 v40, v40, v41
	s_waitcnt lgkmcnt(0)
	v_add_f32_e32 v48, v48, v49
	s_nop 1
	v_mov_b32_dpp v49, v48 quad_perm:[2,3,0,1] row_mask:0xf bank_mask:0xf
	v_cvt_pk_bf16_f32 v41, v42, v43
	v_cvt_pk_bf16_f32 v32, v32, v33
	v_cvt_pk_bf16_f32 v33, v34, v35
	s_waitcnt lgkmcnt(0)
	v_add_f32_e32 v50, v48, v49
	s_nop 1
	v_mov_b32_dpp v51, v50 row_half_mirror row_mask:0xf bank_mask:0xf
	v_lshl_add_u64 v[48:49], v[64:65], 0, s[6:7]
	global_store_dwordx2 v[48:49], v[44:45], off
	global_store_dwordx2 v[48:49], v[40:41], off offset:512
	v_cvt_pk_bf16_f32 v40, v36, v37
	s_waitcnt lgkmcnt(0)
	v_add_f32_e32 v50, v50, v51
	s_nop 1
	v_mov_b32_dpp v51, v50 row_mirror row_mask:0xf bank_mask:0xf
	v_cvt_pk_bf16_f32 v41, v38, v39
	global_store_dwordx2 v[48:49], v[40:41], off offset:1024
	global_store_dwordx2 v[48:49], v[32:33], off offset:1536
	s_waitcnt lgkmcnt(0)
	v_add_f32_e32 v44, v50, v51
	ds_bpermute_b32 v45, v72, v44
	s_waitcnt lgkmcnt(0)
	v_add_f32_e32 v36, v44, v45
	ds_bpermute_b32 v37, v73, v36
	s_and_saveexec_b64 s[6:7], vcc
	s_cbranch_execz .LBB0_79
	s_lshl_b64 s[14:15], s[4:5], 2
	s_add_u32 s14, s8, s14
	s_waitcnt lgkmcnt(0)
	v_add_f32_e32 v32, v36, v37
	s_addc_u32 s15, s9, s15
	global_store_dword v169, v32, s[14:15]
.LBB0_79:
	s_or_b64 exec, exec, s[6:7]
	v_mul_f32_e32 v32, v13, v13
	v_mul_f32_e32 v33, v15, v15
	v_fmac_f32_e32 v32, v12, v12
	v_fmac_f32_e32 v33, v14, v14
	v_add_f32_e32 v32, v32, v33
	v_mul_f32_e32 v33, v9, v9
	v_mul_f32_e32 v34, v11, v11
	v_fmac_f32_e32 v33, v8, v8
	v_fmac_f32_e32 v34, v10, v10
	v_add_f32_e32 v33, v33, v34
	v_add_f32_e32 v32, v32, v33
	v_mul_f32_e32 v33, v5, v5
	v_mul_f32_e32 v34, v7, v7
	v_fmac_f32_e32 v33, v4, v4
	v_fmac_f32_e32 v34, v6, v6
	v_add_f32_e32 v33, v33, v34
	v_add_f32_e32 v32, v32, v33
	v_mul_f32_e32 v33, v1, v1
	v_mul_f32_e32 v34, v3, v3
	v_fmac_f32_e32 v33, v0, v0
	v_fmac_f32_e32 v34, v2, v2
	v_add_f32_e32 v33, v33, v34
	v_add_f32_e32 v32, v32, v33
	s_nop 1
	v_mov_b32_dpp v33, v32 quad_perm:[1,0,3,2] row_mask:0xf bank_mask:0xf
	s_lshl_b64 s[4:5], s[4:5], 11
	v_cvt_pk_bf16_f32 v28, v28, v29
	v_cvt_pk_bf16_f32 v29, v30, v31
	v_cvt_pk_bf16_f32 v24, v24, v25
	s_waitcnt lgkmcnt(0)
	v_add_f32_e32 v32, v32, v33
	s_nop 1
	v_mov_b32_dpp v33, v32 quad_perm:[2,3,0,1] row_mask:0xf bank_mask:0xf
	v_cvt_pk_bf16_f32 v25, v26, v27
	v_cvt_pk_bf16_f32 v16, v16, v17
	v_cvt_pk_bf16_f32 v17, v18, v19
	s_waitcnt lgkmcnt(0)
	v_add_f32_e32 v34, v32, v33
	s_nop 1
	v_mov_b32_dpp v35, v34 row_half_mirror row_mask:0xf bank_mask:0xf
	v_lshl_add_u64 v[32:33], v[64:65], 0, s[4:5]
	global_store_dwordx2 v[32:33], v[28:29], off
	global_store_dwordx2 v[32:33], v[24:25], off offset:512
	v_cvt_pk_bf16_f32 v24, v20, v21
	s_waitcnt lgkmcnt(0)
	v_add_f32_e32 v34, v34, v35
	s_nop 1
	v_mov_b32_dpp v35, v34 row_mirror row_mask:0xf bank_mask:0xf
	v_cvt_pk_bf16_f32 v25, v22, v23
	global_store_dwordx2 v[32:33], v[24:25], off offset:1024
	global_store_dwordx2 v[32:33], v[16:17], off offset:1536
	s_waitcnt lgkmcnt(0)
	v_add_f32_e32 v28, v34, v35
	ds_bpermute_b32 v29, v72, v28
	s_waitcnt lgkmcnt(0)
	v_add_f32_e32 v20, v28, v29
	ds_bpermute_b32 v21, v73, v20
	s_and_saveexec_b64 s[4:5], vcc
	s_cbranch_execz .LBB0_48
	s_lshl_b64 s[6:7], s[0:1], 2
	s_add_u32 s6, s8, s6
	s_waitcnt lgkmcnt(0)
	v_add_f32_e32 v16, v20, v21
	s_addc_u32 s7, s9, s7
	global_store_dword v169, v16, s[6:7]
	s_branch .LBB0_48
